# GQA attention QK phases: 3 extra K-fragment buffers (deeper ds_read prefetch), VALU spread evenly over MFMA gaps
# baseline (speedup 1.0000x reference)
; __device__ __forceinline__ void finishSM(f32x16& p0, f32x16& p1, float alpha, float& l_reg, bf16x8& pa0, bf16x8& pa1, bf16x8& pa2, bf16x8& pa3) {
; #pragma unroll
;   for (int r = 0; r < 16; ++r) p1[r] = __builtin_amdgcn_exp2f(p1[r]);
;   float ps = 0;
; #pragma unroll
;   for (int r = 0; r < 16; ++r) ps += p0[r];
; #pragma unroll
;   for (int r = 0; r < 16; ++r) ps += p1[r];
;   { auto rr = __builtin_amdgcn_permlane32_swap(__float_as_uint(ps), __float_as_uint(ps), false, false);
;     ps = __uint_as_float(rr[0]) + __uint_as_float(rr[1]); }
;   l_reg = l_reg * alpha + ps;
;     ...
;   PK4(p0, 0, pa0); PK4(p0, 8, pa1); PK4(p1, 0, pa2); PK4(p1, 8, pa3);
;     ...
; }
; template <int DK, int NPARK>
; __device__ __forceinline__ void qkt(f32x16& p0, f32x16& p1, const char* Ks, const bf16x8* qr, const char* qpark, int r32, int hi) {
;   p0 = f32x16{}; p1 = f32x16{};
; #pragma unroll
;   for (int d0 = 0; d0 < DK / 16; ++d0) { const int cb = (d0 * 16 + hi * 8) * 2;
;     bf16x8 b0 = *reinterpret_cast<const bf16x8*>(Ks + kswz<DK>(r32, cb));
;     bf16x8 b1 = *reinterpret_cast<const bf16x8*>(Ks + kswz<DK>(32 + r32, cb));
;     bf16x8 q;
;     if constexpr (NPARK > 0) { if (d0 >= DK / 16 - NPARK) q = *reinterpret_cast<const bf16x8*>(qpark + (d0 - (DK / 16 - NPARK)) * 1024); else q = qr[d0]; } else q = qr[d0];
;     p0 = __builtin_amdgcn_mfma_f32_32x32x16_bf16(b0, q, p0, 0, 0, 0);
;     p1 = __builtin_amdgcn_mfma_f32_32x32x16_bf16(b1, q, p1, 0, 0, 0); }
; }
.LBB0_924:
	ds_read_b128 v[64:67], v161 offset:49152
	ds_read_b128 v[68:71], v161 offset:57344
	ds_read_b128 v[194:197], v170 offset:49152
	ds_read_b128 v[198:201], v170 offset:57344
	ds_read_b128 v[214:217], v169 offset:49152
	ds_read_b128 v[218:221], v169 offset:57344
	ds_read_b128 v[222:225], v168 offset:49152
	ds_read_b128 v[226:229], v168 offset:57344
	v_add_f32_e32 v144, 0, v145
	v_add_f32_e32 v144, v187, v144
	s_waitcnt lgkmcnt(7)
	v_mfma_f32_32x32x16_bf16 v[80:95], v[64:67], v[112:115], 0
	v_add_f32_e32 v144, v146, v144
	v_add_f32_e32 v144, v188, v144
	v_add_f32_e32 v144, v186, v144
	v_add_f32_e32 v144, v189, v144
	s_waitcnt lgkmcnt(6)
	v_mfma_f32_32x32x16_bf16 v[64:79], v[68:71], v[112:115], 0
	ds_read_b128 v[230:233], v167 offset:49152
	ds_read_b128 v[234:237], v167 offset:57344
	v_add_f32_e32 v144, v147, v144
	v_add_f32_e32 v144, v185, v144
	v_add_f32_e32 v144, v157, v144
	v_add_f32_e32 v144, v181, v144
	v_add_f32_e32 v144, v179, v144
	s_waitcnt lgkmcnt(7)
	v_mfma_f32_32x32x16_bf16 v[80:95], v[194:197], v[108:111], v[80:95]
	v_add_f32_e32 v144, v182, v144
	v_exp_f32_e32 v142, v142
	v_add_f32_e32 v144, v154, v144
	v_exp_f32_e32 v143, v143
	s_waitcnt lgkmcnt(6)
	v_mfma_f32_32x32x16_bf16 v[64:79], v[198:201], v[108:111], v[64:79]
	v_add_f32_e32 v144, v155, v144
	v_exp_f32_e32 v140, v140
	v_add_f32_e32 v144, v156, v144
	v_exp_f32_e32 v141, v141
	s_waitcnt lgkmcnt(5)
	v_mfma_f32_32x32x16_bf16 v[80:95], v[214:217], v[120:123], v[80:95]
	v_add_f32_e32 v144, v180, v144
	v_exp_f32_e32 v136, v136
	v_add_f32_e32 v144, v142, v144
	v_exp_f32_e32 v137, v137
	s_waitcnt lgkmcnt(4)
	v_mfma_f32_32x32x16_bf16 v[64:79], v[218:221], v[120:123], v[64:79]
	ds_read_b128 v[214:217], v166 offset:49152
	ds_read_b128 v[218:221], v166 offset:57344
	v_add_f32_e32 v144, v143, v144
	v_exp_f32_e32 v132, v132
	v_add_f32_e32 v144, v140, v144
	s_waitcnt lgkmcnt(5)
	v_mfma_f32_32x32x16_bf16 v[80:95], v[222:225], v[124:127], v[80:95]
	v_exp_f32_e32 v133, v133
	v_add_f32_e32 v144, v141, v144
	v_exp_f32_e32 v130, v130
	v_add_f32_e32 v144, v136, v144
	s_waitcnt lgkmcnt(4)
	v_mfma_f32_32x32x16_bf16 v[64:79], v[226:229], v[124:127], v[64:79]
	ds_read_b128 v[222:225], v172 offset:49152
	ds_read_b128 v[226:229], v172 offset:57344
	v_exp_f32_e32 v131, v131
	v_add_f32_e32 v144, v137, v144
	v_exp_f32_e32 v138, v138
	v_add_f32_e32 v144, v132, v144
	s_waitcnt lgkmcnt(5)
	v_mfma_f32_32x32x16_bf16 v[80:95], v[230:233], v[116:119], v[80:95]
	v_exp_f32_e32 v139, v139
	v_add_f32_e32 v144, v133, v144
	v_exp_f32_e32 v134, v134
	v_add_f32_e32 v144, v130, v144
	s_waitcnt lgkmcnt(4)
	v_mfma_f32_32x32x16_bf16 v[64:79], v[234:237], v[116:119], v[64:79]
	ds_read_b128 v[230:233], v171 offset:49152
	ds_read_b128 v[234:237], v171 offset:57344
	v_exp_f32_e32 v135, v135
	v_add_f32_e32 v144, v131, v144
	v_exp_f32_e32 v128, v128
	s_waitcnt lgkmcnt(5)
	v_mfma_f32_32x32x16_bf16 v[80:95], v[214:217], v[104:107], v[80:95]
	v_add_f32_e32 v144, v138, v144
	v_exp_f32_e32 v129, v129
	v_add_f32_e32 v144, v139, v144
	v_add_f32_e32 v144, v134, v144
	v_add_f32_e32 v144, v135, v144
	s_waitcnt lgkmcnt(4)
	v_mfma_f32_32x32x16_bf16 v[64:79], v[218:221], v[104:107], v[64:79]
	v_add_f32_e32 v144, v128, v144
	v_add_f32_e32 v175, v129, v144
	v_mov_b32_e32 v176, v175
	s_nop 1
	v_permlane32_swap_b32_e32 v175, v176
	v_cvt_pk_bf16_f32 v144, v145, v187
	v_cvt_pk_bf16_f32 v145, v146, v188
	s_waitcnt lgkmcnt(3)
	v_mfma_f32_32x32x16_bf16 v[80:95], v[222:225], v[100:103], v[80:95]
	v_cvt_pk_bf16_f32 v146, v186, v189
	v_cvt_pk_bf16_f32 v147, v147, v185
	v_cvt_pk_bf16_f32 v184, v157, v181
	v_cvt_pk_bf16_f32 v185, v179, v182
	v_permlane32_swap_b32_e32 v144, v146
	s_waitcnt lgkmcnt(2)
	v_mfma_f32_32x32x16_bf16 v[64:79], v[226:229], v[100:103], v[64:79]
	v_cvt_pk_bf16_f32 v186, v154, v155
	v_cvt_pk_bf16_f32 v187, v156, v180
	v_cvt_pk_bf16_f32 v180, v142, v143
	v_cvt_pk_bf16_f32 v181, v140, v141
	v_cvt_pk_bf16_f32 v182, v136, v137
	v_cvt_pk_bf16_f32 v183, v132, v133
	s_waitcnt lgkmcnt(1)
	v_mfma_f32_32x32x16_bf16 v[80:95], v[230:233], v[96:99], v[80:95]
	v_cvt_pk_bf16_f32 v188, v130, v131
	v_cvt_pk_bf16_f32 v189, v138, v139
	v_cvt_pk_bf16_f32 v190, v134, v135
	v_cvt_pk_bf16_f32 v191, v128, v129
	v_permlane32_swap_b32_e32 v145, v147
	s_waitcnt lgkmcnt(0)
	v_mfma_f32_32x32x16_bf16 v[64:79], v[234:237], v[96:99], v[64:79]
	v_permlane32_swap_b32_e32 v184, v186
	v_permlane32_swap_b32_e32 v185, v187
	v_permlane32_swap_b32_e32 v180, v182
	v_permlane32_swap_b32_e32 v181, v183
	v_permlane32_swap_b32_e32 v188, v190
	v_permlane32_swap_b32_e32 v189, v191
	v_lshl_add_u64 v[154:155], s[10:11], 0, v[192:193]
	v_add_co_u32_e32 v128, vcc, s0, v154
	v_lshl_add_u64 v[156:157], s[10:11], 0, v[152:153]
	s_nop 0
	v_addc_co_u32_e32 v129, vcc, 0, v155, vcc
	v_add_co_u32_e32 v132, vcc, s0, v156
	s_nop 1
	v_addc_co_u32_e32 v133, vcc, 0, v157, vcc
	v_add_co_u32_e32 v136, vcc, s67, v154
	global_load_dwordx4 v[128:131], v[128:129], off
	s_nop 0
	global_load_dwordx4 v[132:135], v[132:133], off
	v_addc_co_u32_e32 v137, vcc, 0, v155, vcc
	v_add_co_u32_e32 v140, vcc, s67, v156
	s_nop 1
	v_addc_co_u32_e32 v141, vcc, 0, v157, vcc
	global_load_dwordx4 v[136:139], v[136:137], off
	s_nop 0
	global_load_dwordx4 v[140:143], v[140:141], off
	ds_read_b64_tr_b16 v[194:195], v160 offset:0
	ds_read_b64_tr_b16 v[196:197], v160 offset:0x800
	ds_read_b64_tr_b16 v[198:199], v160 offset:0x1000
	ds_read_b64_tr_b16 v[200:201], v160 offset:0x1800
	ds_read_b64_tr_b16 v[202:203], v160 offset:0x2000
	ds_read_b64_tr_b16 v[204:205], v160 offset:0x2800
	ds_read_b64_tr_b16 v[206:207], v160 offset:0x3000
	ds_read_b64_tr_b16 v[208:209], v160 offset:0x3800
	s_waitcnt lgkmcnt(0)
; #define SBAR() __builtin_amdgcn_sched_barrier(0)
; template <int DK>
; __device__ __forceinline__ void partialSM(f32x16& p0, f32x16& p1, float& m_reg, float& mn, float& alpha) {
;   constexpr float SCALE = Cst<DK>::SCALE, C = SCALE * 1.4426950408889634f;
;   float pmax = p0[0];
; #pragma unroll
;   for (int r = 1; r < 16; ++r) pmax = fmaxf(pmax, p0[r]);
; #pragma unroll
;   for (int r = 0; r < 16; ++r) pmax = fmaxf(pmax, p1[r]);
;   { auto rr = __builtin_amdgcn_permlane32_swap(__float_as_uint(pmax), __float_as_uint(pmax), false, false);
;     pmax = fmaxf(__uint_as_float(rr[0]), __uint_as_float(rr[1])); }
;   if (__builtin_expect(__all(pmax - m_reg <= THR / SCALE), 1)) { mn = m_reg; alpha = 1.f; }
;   else { mn = fmaxf(m_reg, pmax); alpha = __builtin_amdgcn_exp2f((m_reg - mn) * C); m_reg = mn; }
; template <int OFF> __device__ __forceinline__ s16x4 tr_read(int vb) {
;   s16x4 r; asm volatile("ds_read_b64_tr_b16 %0, %1 offset:%2" : "=&v"(r) : "v"(vb), "i"(OFF) : "memory"); return r;
; }
; template <int D0> __device__ __forceinline__ void pv_one(f32x16& od, int vb, bf16x8 pa0, bf16x8 pa1, bf16x8 pa2, bf16x8 pa3) {
;   const s16x4 l0 = tr_read<v_rd_off(D0, 0, 0)>(vb), h0 = tr_read<v_rd_off(D0, 0, 1)>(vb), l1 = tr_read<v_rd_off(D0, 1, 0)>(vb), h1 = tr_read<v_rd_off(D0, 1, 1)>(vb);
;   const s16x4 l2 = tr_read<v_rd_off(D0, 2, 0)>(vb), h2 = tr_read<v_rd_off(D0, 2, 1)>(vb), l3 = tr_read<v_rd_off(D0, 3, 0)>(vb), h3 = tr_read<v_rd_off(D0, 3, 1)>(vb);
;   asm volatile("s_waitcnt lgkmcnt(0)" ::: "memory"); SBAR();
;     ...
;   od = __builtin_amdgcn_mfma_f32_32x32x16_bf16(pa0, PK(l0, h0), od, 0, 0, 0);
;   od = __builtin_amdgcn_mfma_f32_32x32x16_bf16(pa1, PK(l1, h1), od, 0, 0, 0);
;   od = __builtin_amdgcn_mfma_f32_32x32x16_bf16(pa2, PK(l2, h2), od, 0, 0, 0);
;   od = __builtin_amdgcn_mfma_f32_32x32x16_bf16(pa3, PK(l3, h3), od, 0, 0, 0);
;     ...
; }
; __device__ __forceinline__ void pv_d0(f32x16* o, int vb, bf16x8 pa0, bf16x8 pa1, bf16x8 pa2, bf16x8 pa3) {
;   pv_one<0>(o[0], vb, pa0, pa1, pa2, pa3); pv_one<1>(o[1], vb, pa0, pa1, pa2, pa3); pv_one<2>(o[2], vb, pa0, pa1, pa2, pa3); pv_one<3>(o[3], vb, pa0, pa1, pa2, pa3);
	s_nop 0
	v_mfma_f32_32x32x16_bf16 v[0:15], v[144:147], v[194:197], v[0:15]
	ds_read_b64_tr_b16 v[194:195], v160 offset:0x200
	ds_read_b64_tr_b16 v[196:197], v160 offset:0xa00
	v_mfma_f32_32x32x16_bf16 v[0:15], v[184:187], v[198:201], v[0:15]
	ds_read_b64_tr_b16 v[198:199], v160 offset:0x1200
	ds_read_b64_tr_b16 v[200:201], v160 offset:0x1a00
	v_mfma_f32_32x32x16_bf16 v[0:15], v[180:183], v[202:205], v[0:15]
	ds_read_b64_tr_b16 v[202:203], v160 offset:0x2200
	ds_read_b64_tr_b16 v[204:205], v160 offset:0x2a00
	v_mfma_f32_32x32x16_bf16 v[0:15], v[188:191], v[206:209], v[0:15]
	ds_read_b64_tr_b16 v[206:207], v160 offset:0x3200
	ds_read_b64_tr_b16 v[208:209], v160 offset:0x3a00
	s_waitcnt lgkmcnt(0)
	v_mfma_f32_32x32x16_bf16 v[48:63], v[144:147], v[194:197], v[48:63]
	ds_read_b64_tr_b16 v[194:195], v160 offset:0x400
	ds_read_b64_tr_b16 v[196:197], v160 offset:0xc00
	v_mfma_f32_32x32x16_bf16 v[48:63], v[184:187], v[198:201], v[48:63]
	ds_read_b64_tr_b16 v[198:199], v160 offset:0x1400
	ds_read_b64_tr_b16 v[200:201], v160 offset:0x1c00
	v_mfma_f32_32x32x16_bf16 v[48:63], v[180:183], v[202:205], v[48:63]
	ds_read_b64_tr_b16 v[202:203], v160 offset:0x2400
	ds_read_b64_tr_b16 v[204:205], v160 offset:0x2c00
	v_mfma_f32_32x32x16_bf16 v[48:63], v[188:191], v[206:209], v[48:63]
	ds_read_b64_tr_b16 v[206:207], v160 offset:0x3400
	ds_read_b64_tr_b16 v[208:209], v160 offset:0x3c00
	s_waitcnt lgkmcnt(0)
	v_mfma_f32_32x32x16_bf16 v[32:47], v[144:147], v[194:197], v[32:47]
	ds_read_b64_tr_b16 v[194:195], v160 offset:0x600
	ds_read_b64_tr_b16 v[196:197], v160 offset:0xe00
	v_mfma_f32_32x32x16_bf16 v[32:47], v[184:187], v[198:201], v[32:47]
	ds_read_b64_tr_b16 v[198:199], v160 offset:0x1600
	ds_read_b64_tr_b16 v[200:201], v160 offset:0x1e00
	v_mfma_f32_32x32x16_bf16 v[32:47], v[180:183], v[202:205], v[32:47]
	ds_read_b64_tr_b16 v[202:203], v160 offset:0x2600
	ds_read_b64_tr_b16 v[204:205], v160 offset:0x2e00
	v_mfma_f32_32x32x16_bf16 v[32:47], v[188:191], v[206:209], v[32:47]
	ds_read_b64_tr_b16 v[206:207], v160 offset:0x3600
	ds_read_b64_tr_b16 v[208:209], v160 offset:0x3e00
	s_waitcnt lgkmcnt(0)
	v_mfma_f32_32x32x16_bf16 v[16:31], v[144:147], v[194:197], v[16:31]
	v_max_f32_e32 v144, v81, v81
	v_max_f32_e32 v145, v80, v80
	v_max_f32_e32 v144, v145, v144
	v_max3_f32 v144, v144, v82, v83
	v_max3_f32 v144, v144, v84, v85
	v_max3_f32 v144, v144, v86, v87
	v_max3_f32 v144, v144, v88, v89
	v_max3_f32 v144, v144, v90, v91
	v_max3_f32 v144, v144, v92, v93
	v_mfma_f32_32x32x16_bf16 v[16:31], v[184:187], v[198:201], v[16:31]
	v_max3_f32 v144, v144, v94, v95
	v_max3_f32 v144, v144, v64, v65
	v_max3_f32 v144, v144, v66, v67
	v_max3_f32 v144, v144, v68, v69
	v_max3_f32 v144, v144, v70, v71
	v_max3_f32 v144, v144, v72, v73
	v_max3_f32 v144, v144, v74, v75
	v_max3_f32 v144, v144, v76, v77
	v_mfma_f32_32x32x16_bf16 v[16:31], v[180:183], v[202:205], v[16:31]
	v_max3_f32 v144, v144, v78, v79
	v_mov_b32_e32 v145, v144
	s_nop 1
	v_permlane32_swap_b32_e32 v144, v145
	v_max_f32_e32 v145, v145, v145
	v_max_f32_e32 v144, v144, v144
	v_max_f32_e32 v144, v144, v145
	v_sub_f32_e32 v145, v144, v174
	v_cmp_ge_f32_e32 vcc, s1, v145
	v_max_f32_e32 v145, v174, v174
	v_max_f32_e32 v144, v145, v144
	v_mfma_f32_32x32x16_bf16 v[16:31], v[188:191], v[206:209], v[16:31]
	v_sub_f32_e32 v145, v174, v144
	v_mul_f32_e32 v145, 0x3e0293ee, v145
	v_exp_f32_e32 v145, v145
	s_cmp_eq_u64 vcc, exec
	s_cselect_b64 s[8:9], -1, 0
	s_barrier
	s_waitcnt vmcnt(0)
	v_cndmask_b32_e64 v177, v145, 1.0, s[8:9]
	v_cmp_gt_f32_e32 vcc, 1.0, v177
	s_waitcnt vmcnt(3)
	ds_write_b128 v164, v[128:131]
	s_waitcnt vmcnt(2)
	ds_write_b128 v165, v[132:135]
	s_waitcnt vmcnt(1)
	ds_write_b128 v162, v[136:139] offset:32768
	s_waitcnt vmcnt(0)
	ds_write_b128 v163, v[140:143] offset:32768
	s_cbranch_vccz .LBB0_928
	s_and_saveexec_b64 s[12:13], s[6:7]
	ds_write_b32 v151, v177 offset:128
	s_or_b64 exec, exec, s[12:13]
	s_waitcnt lgkmcnt(0)
	v_add_u32_e32 v140, s95, v150
	ds_read_b128 v[128:131], v140 offset:224
	ds_read_b128 v[132:135], v140 offset:192
	ds_read_b128 v[136:139], v140 offset:160
	ds_read_b128 v[140:143], v140 offset:128
	s_waitcnt lgkmcnt(3)
	v_pk_mul_f32 v[12:13], v[12:13], v[128:129]
	s_waitcnt lgkmcnt(2)
	v_pk_mul_f32 v[8:9], v[8:9], v[132:133]
	s_waitcnt lgkmcnt(1)
	v_pk_mul_f32 v[4:5], v[4:5], v[136:137]
	v_pk_mul_f32 v[14:15], v[14:15], v[130:131]
	v_pk_mul_f32 v[10:11], v[10:11], v[134:135]
	v_pk_mul_f32 v[6:7], v[6:7], v[138:139]
	s_waitcnt lgkmcnt(0)
	v_pk_mul_f32 v[2:3], v[2:3], v[142:143]
	v_pk_mul_f32 v[0:1], v[0:1], v[140:141]
	v_pk_mul_f32 v[60:61], v[60:61], v[128:129]
	v_pk_mul_f32 v[56:57], v[56:57], v[132:133]
	v_pk_mul_f32 v[52:53], v[52:53], v[136:137]
	v_pk_mul_f32 v[62:63], v[62:63], v[130:131]
	v_pk_mul_f32 v[58:59], v[58:59], v[134:135]
	v_pk_mul_f32 v[54:55], v[54:55], v[138:139]
	v_pk_mul_f32 v[50:51], v[50:51], v[142:143]
	v_pk_mul_f32 v[48:49], v[48:49], v[140:141]
	v_pk_mul_f32 v[44:45], v[44:45], v[128:129]
	v_pk_mul_f32 v[40:41], v[40:41], v[132:133]
	v_pk_mul_f32 v[36:37], v[36:37], v[136:137]
	v_pk_mul_f32 v[46:47], v[46:47], v[130:131]
	v_pk_mul_f32 v[42:43], v[42:43], v[134:135]
	v_pk_mul_f32 v[38:39], v[38:39], v[138:139]
	v_pk_mul_f32 v[34:35], v[34:35], v[142:143]
	v_pk_mul_f32 v[32:33], v[32:33], v[140:141]
	v_pk_mul_f32 v[28:29], v[28:29], v[128:129]
	v_pk_mul_f32 v[24:25], v[24:25], v[132:133]
	v_pk_mul_f32 v[20:21], v[20:21], v[136:137]
	v_pk_mul_f32 v[30:31], v[30:31], v[130:131]
	v_pk_mul_f32 v[26:27], v[26:27], v[134:135]
	v_pk_mul_f32 v[22:23], v[22:23], v[138:139]
	v_pk_mul_f32 v[18:19], v[18:19], v[142:143]
	v_pk_mul_f32 v[16:17], v[16:17], v[140:141]
; template <int DK>
; __device__ __forceinline__ void partialSM(f32x16& p0, f32x16& p1, float& m_reg, float& mn, float& alpha) {
;     ...
;   if (__builtin_expect(__all(pmax - m_reg <= THR / SCALE), 1)) { mn = m_reg; alpha = 1.f; }
;   else { mn = fmaxf(m_reg, pmax); alpha = __builtin_amdgcn_exp2f((m_reg - mn) * C); m_reg = mn; }
;   float mnC = -mn * C;
; #pragma unroll
;   for (int r = 0; r < 16; ++r) p0[r] = fmaf(p0[r], C, mnC);
; #pragma unroll
;   for (int r = 0; r < 16; ++r) p1[r] = fmaf(p1[r], C, mnC);
; #pragma unroll
;   for (int r = 0; r < 16; ++r) p0[r] = __builtin_amdgcn_exp2f(p0[r]);
; }
; __device__ __forceinline__ void finishSM(f32x16& p0, f32x16& p1, float alpha, float& l_reg, bf16x8& pa0, bf16x8& pa1, bf16x8& pa2, bf16x8& pa3) {
; #pragma unroll
;   for (int r = 0; r < 16; ++r) p1[r] = __builtin_amdgcn_exp2f(p1[r]);
;   float ps = 0;
; #pragma unroll
;   for (int r = 0; r < 16; ++r) ps += p0[r];
; #pragma unroll
;   for (int r = 0; r < 16; ++r) ps += p1[r];
;   { auto rr = __builtin_amdgcn_permlane32_swap(__float_as_uint(ps), __float_as_uint(ps), false, false);
;     ps = __uint_as_float(rr[0]) + __uint_as_float(rr[1]); }
;   l_reg = l_reg * alpha + ps;
;     ...
;   PK4(p0, 0, pa0); PK4(p0, 8, pa1); PK4(p1, 0, pa2); PK4(p1, 8, pa3);
;     ...
; }
; template <int DK, int NPARK>
; __device__ __forceinline__ void qkt(f32x16& p0, f32x16& p1, const char* Ks, const bf16x8* qr, const char* qpark, int r32, int hi) {
;   p0 = f32x16{}; p1 = f32x16{};
; #pragma unroll
;   for (int d0 = 0; d0 < DK / 16; ++d0) { const int cb = (d0 * 16 + hi * 8) * 2;
;     bf16x8 b0 = *reinterpret_cast<const bf16x8*>(Ks + kswz<DK>(r32, cb));
;     bf16x8 b1 = *reinterpret_cast<const bf16x8*>(Ks + kswz<DK>(32 + r32, cb));
;     bf16x8 q;
;     if constexpr (NPARK > 0) { if (d0 >= DK / 16 - NPARK) q = *reinterpret_cast<const bf16x8*>(qpark + (d0 - (DK / 16 - NPARK)) * 1024); else q = qr[d0]; } else q = qr[d0];
;     p0 = __builtin_amdgcn_mfma_f32_32x32x16_bf16(b0, q, p0, 0, 0, 0);
;     p1 = __builtin_amdgcn_mfma_f32_32x32x16_bf16(b1, q, p1, 0, 0, 0); }
; }
.LBB0_928:
	v_cndmask_b32_e64 v174, v144, v174, s[8:9]
	v_mul_f32_e32 v144, 0xbe0293ee, v174
	v_fmamk_f32 v80, v80, 0x3e0293ee, v144
	v_fmamk_f32 v81, v81, 0x3e0293ee, v144
	v_fmamk_f32 v82, v82, 0x3e0293ee, v144
	v_fmamk_f32 v83, v83, 0x3e0293ee, v144
	v_fmamk_f32 v84, v84, 0x3e0293ee, v144
	v_fmamk_f32 v85, v85, 0x3e0293ee, v144
	v_fmamk_f32 v86, v86, 0x3e0293ee, v144
	v_fmamk_f32 v87, v87, 0x3e0293ee, v144
	v_fmamk_f32 v88, v88, 0x3e0293ee, v144
	v_fmamk_f32 v89, v89, 0x3e0293ee, v144
	v_fmamk_f32 v90, v90, 0x3e0293ee, v144
	v_fmamk_f32 v91, v91, 0x3e0293ee, v144
	v_fmamk_f32 v92, v92, 0x3e0293ee, v144
	v_fmamk_f32 v93, v93, 0x3e0293ee, v144
	v_fmamk_f32 v94, v94, 0x3e0293ee, v144
	v_fmamk_f32 v95, v95, 0x3e0293ee, v144
	v_fmamk_f32 v184, v64, 0x3e0293ee, v144
	v_fmamk_f32 v185, v65, 0x3e0293ee, v144
	v_fmamk_f32 v186, v66, 0x3e0293ee, v144
	v_fmamk_f32 v187, v67, 0x3e0293ee, v144
	v_fmamk_f32 v188, v68, 0x3e0293ee, v144
	v_fmamk_f32 v146, v69, 0x3e0293ee, v144
	v_fmamk_f32 v147, v70, 0x3e0293ee, v144
	v_fmamk_f32 v179, v71, 0x3e0293ee, v144
	v_fmamk_f32 v180, v72, 0x3e0293ee, v144
	v_fmamk_f32 v181, v73, 0x3e0293ee, v144
	v_fmamk_f32 v182, v74, 0x3e0293ee, v144
	v_fmamk_f32 v183, v75, 0x3e0293ee, v144
	v_fmamk_f32 v145, v76, 0x3e0293ee, v144
	v_fmamk_f32 v189, v77, 0x3e0293ee, v144
	v_fmamk_f32 v190, v78, 0x3e0293ee, v144
	v_fmac_f32_e32 v144, 0x3e0293ee, v79
	v_exp_f32_e32 v141, v80
	v_exp_f32_e32 v143, v81
	v_exp_f32_e32 v139, v82
	v_exp_f32_e32 v142, v83
	v_exp_f32_e32 v138, v84
	v_exp_f32_e32 v140, v85
	v_exp_f32_e32 v136, v86
	v_exp_f32_e32 v137, v87
	v_exp_f32_e32 v133, v88
	v_exp_f32_e32 v135, v89
	v_exp_f32_e32 v132, v90
	v_exp_f32_e32 v134, v91
	v_exp_f32_e32 v129, v92
	v_exp_f32_e32 v131, v93
	v_exp_f32_e32 v128, v94
	v_exp_f32_e32 v130, v95
	s_waitcnt lgkmcnt(0)
	s_barrier
	ds_read_b128 v[64:67], v161 offset:32768
	ds_read_b128 v[68:71], v161 offset:40960
	ds_read_b128 v[194:197], v170 offset:32768
	ds_read_b128 v[198:201], v170 offset:40960
	ds_read_b128 v[214:217], v169 offset:32768
	ds_read_b128 v[218:221], v169 offset:40960
	ds_read_b128 v[222:225], v168 offset:32768
	ds_read_b128 v[226:229], v168 offset:40960
	v_exp_f32_e32 v203, v144
	v_add_f32_e32 v144, 0, v141
	s_waitcnt lgkmcnt(7)
	v_mfma_f32_32x32x16_bf16 v[80:95], v[64:67], v[112:115], 0
	v_add_f32_e32 v144, v143, v144
	v_add_f32_e32 v144, v139, v144
	v_add_f32_e32 v144, v142, v144
	s_waitcnt lgkmcnt(6)
	v_mfma_f32_32x32x16_bf16 v[64:79], v[68:71], v[112:115], 0
	ds_read_b128 v[230:233], v167 offset:32768
	ds_read_b128 v[234:237], v167 offset:40960
	v_add_f32_e32 v144, v138, v144
	v_add_f32_e32 v144, v140, v144
	v_add_f32_e32 v144, v136, v144
	v_add_f32_e32 v144, v137, v144
	v_add_f32_e32 v144, v133, v144
	s_waitcnt lgkmcnt(7)
	v_mfma_f32_32x32x16_bf16 v[80:95], v[194:197], v[108:111], v[80:95]
	v_add_f32_e32 v144, v135, v144
	v_add_f32_e32 v144, v132, v144
	v_add_f32_e32 v144, v134, v144
	v_exp_f32_e32 v191, v184
	v_add_f32_e32 v144, v129, v144
	s_waitcnt lgkmcnt(6)
	v_mfma_f32_32x32x16_bf16 v[64:79], v[198:201], v[108:111], v[64:79]
	v_exp_f32_e32 v185, v185
	v_add_f32_e32 v144, v131, v144
	v_add_f32_e32 v144, v128, v144
	v_add_f32_e32 v144, v130, v144
	v_add_f32_e32 v144, v191, v144
	s_waitcnt lgkmcnt(5)
	v_mfma_f32_32x32x16_bf16 v[80:95], v[214:217], v[120:123], v[80:95]
	v_add_f32_e32 v144, v185, v144
	v_exp_f32_e32 v179, v179
	v_exp_f32_e32 v180, v180
	s_waitcnt lgkmcnt(4)
	v_mfma_f32_32x32x16_bf16 v[64:79], v[218:221], v[120:123], v[64:79]
	ds_read_b128 v[214:217], v166 offset:32768
	ds_read_b128 v[218:221], v166 offset:40960
	v_exp_f32_e32 v181, v181
	v_exp_f32_e32 v182, v182
	v_exp_f32_e32 v202, v189
	s_waitcnt lgkmcnt(5)
	v_mfma_f32_32x32x16_bf16 v[80:95], v[222:225], v[124:127], v[80:95]
	v_exp_f32_e32 v190, v190
	v_exp_f32_e32 v195, v186
	v_exp_f32_e32 v196, v187
	s_waitcnt lgkmcnt(4)
	v_mfma_f32_32x32x16_bf16 v[64:79], v[226:229], v[124:127], v[64:79]
	ds_read_b128 v[222:225], v172 offset:32768
	ds_read_b128 v[226:229], v172 offset:40960
	v_exp_f32_e32 v197, v188
	v_add_f32_e32 v144, v195, v144
	v_add_f32_e32 v144, v196, v144
	v_add_f32_e32 v144, v197, v144
	s_waitcnt lgkmcnt(5)
	v_mfma_f32_32x32x16_bf16 v[80:95], v[230:233], v[116:119], v[80:95]
	v_exp_f32_e32 v198, v146
	v_exp_f32_e32 v199, v147
	v_exp_f32_e32 v200, v183
	s_waitcnt lgkmcnt(4)
	v_mfma_f32_32x32x16_bf16 v[64:79], v[234:237], v[116:119], v[64:79]
	ds_read_b128 v[230:233], v171 offset:32768
	ds_read_b128 v[234:237], v171 offset:40960
	v_exp_f32_e32 v201, v145
	v_add_f32_e32 v144, v198, v144
	v_add_f32_e32 v144, v199, v144
	v_add_f32_e32 v144, v179, v144
	v_add_f32_e32 v144, v180, v144
	s_waitcnt lgkmcnt(5)
	v_mfma_f32_32x32x16_bf16 v[80:95], v[214:217], v[104:107], v[80:95]
	v_add_f32_e32 v144, v181, v144
	v_add_f32_e32 v144, v182, v144
	v_add_f32_e32 v144, v200, v144
	v_add_f32_e32 v144, v201, v144
	v_add_f32_e32 v144, v202, v144
	v_add_f32_e32 v144, v190, v144
	s_waitcnt lgkmcnt(4)
	v_mfma_f32_32x32x16_bf16 v[64:79], v[218:221], v[104:107], v[64:79]
	v_add_f32_e32 v183, v203, v144
	v_mov_b32_e32 v184, v183
	v_cvt_pk_bf16_f32 v144, v141, v143
	v_cvt_pk_bf16_f32 v145, v139, v142
	v_cvt_pk_bf16_f32 v146, v138, v140
	s_waitcnt lgkmcnt(3)
	v_mfma_f32_32x32x16_bf16 v[80:95], v[222:225], v[100:103], v[80:95]
	v_cvt_pk_bf16_f32 v147, v136, v137
	s_nop 1
	v_permlane32_swap_b32_e32 v183, v184
	v_permlane32_swap_b32_e32 v144, v146
	v_permlane32_swap_b32_e32 v145, v147
	v_cvt_pk_bf16_f32 v186, v133, v135
	s_waitcnt lgkmcnt(2)
	v_mfma_f32_32x32x16_bf16 v[64:79], v[226:229], v[100:103], v[64:79]
	v_cvt_pk_bf16_f32 v187, v132, v134
	v_cvt_pk_bf16_f32 v188, v129, v131
	v_cvt_pk_bf16_f32 v189, v128, v130
	v_cvt_pk_bf16_f32 v194, v191, v185
	v_cvt_pk_bf16_f32 v195, v195, v196
	v_cvt_pk_bf16_f32 v196, v197, v198
	s_waitcnt lgkmcnt(1)
; #define SBAR() __builtin_amdgcn_sched_barrier(0)
; template <int DK>
; __device__ __forceinline__ void partialSM(f32x16& p0, f32x16& p1, float& m_reg, float& mn, float& alpha) {
;   constexpr float SCALE = Cst<DK>::SCALE, C = SCALE * 1.4426950408889634f;
;   float pmax = p0[0];
; #pragma unroll
;   for (int r = 1; r < 16; ++r) pmax = fmaxf(pmax, p0[r]);
; #pragma unroll
;   for (int r = 0; r < 16; ++r) pmax = fmaxf(pmax, p1[r]);
;   { auto rr = __builtin_amdgcn_permlane32_swap(__float_as_uint(pmax), __float_as_uint(pmax), false, false);
;     pmax = fmaxf(__uint_as_float(rr[0]), __uint_as_float(rr[1])); }
;   if (__builtin_expect(__all(pmax - m_reg <= THR / SCALE), 1)) { mn = m_reg; alpha = 1.f; }
;   else { mn = fmaxf(m_reg, pmax); alpha = __builtin_amdgcn_exp2f((m_reg - mn) * C); m_reg = mn; }
; template <int OFF> __device__ __forceinline__ s16x4 tr_read(int vb) {
;   s16x4 r; asm volatile("ds_read_b64_tr_b16 %0, %1 offset:%2" : "=&v"(r) : "v"(vb), "i"(OFF) : "memory"); return r;
; }
; template <int D0> __device__ __forceinline__ void pv_one(f32x16& od, int vb, bf16x8 pa0, bf16x8 pa1, bf16x8 pa2, bf16x8 pa3) {
;   const s16x4 l0 = tr_read<v_rd_off(D0, 0, 0)>(vb), h0 = tr_read<v_rd_off(D0, 0, 1)>(vb), l1 = tr_read<v_rd_off(D0, 1, 0)>(vb), h1 = tr_read<v_rd_off(D0, 1, 1)>(vb);
;   const s16x4 l2 = tr_read<v_rd_off(D0, 2, 0)>(vb), h2 = tr_read<v_rd_off(D0, 2, 1)>(vb), l3 = tr_read<v_rd_off(D0, 3, 0)>(vb), h3 = tr_read<v_rd_off(D0, 3, 1)>(vb);
;   asm volatile("s_waitcnt lgkmcnt(0)" ::: "memory"); SBAR();
;     ...
;   od = __builtin_amdgcn_mfma_f32_32x32x16_bf16(pa0, PK(l0, h0), od, 0, 0, 0);
;   od = __builtin_amdgcn_mfma_f32_32x32x16_bf16(pa1, PK(l1, h1), od, 0, 0, 0);
;   od = __builtin_amdgcn_mfma_f32_32x32x16_bf16(pa2, PK(l2, h2), od, 0, 0, 0);
;   od = __builtin_amdgcn_mfma_f32_32x32x16_bf16(pa3, PK(l3, h3), od, 0, 0, 0);
;     ...
; }
; __device__ __forceinline__ void pv_d0(f32x16* o, int vb, bf16x8 pa0, bf16x8 pa1, bf16x8 pa2, bf16x8 pa3) {
;   pv_one<0>(o[0], vb, pa0, pa1, pa2, pa3); pv_one<1>(o[1], vb, pa0, pa1, pa2, pa3); pv_one<2>(o[2], vb, pa0, pa1, pa2, pa3); pv_one<3>(o[3], vb, pa0, pa1, pa2, pa3);
	v_mfma_f32_32x32x16_bf16 v[80:95], v[230:233], v[96:99], v[80:95]
	v_cvt_pk_bf16_f32 v197, v199, v179
	v_cvt_pk_bf16_f32 v198, v180, v181
	v_cvt_pk_bf16_f32 v199, v182, v200
	v_cvt_pk_bf16_f32 v200, v201, v202
	v_cvt_pk_bf16_f32 v201, v190, v203
	s_nop 0
	s_waitcnt lgkmcnt(0)
	v_mfma_f32_32x32x16_bf16 v[64:79], v[234:237], v[96:99], v[64:79]
	v_permlane32_swap_b32_e32 v186, v188
	v_permlane32_swap_b32_e32 v187, v189
	v_permlane32_swap_b32_e32 v194, v196
	v_permlane32_swap_b32_e32 v195, v197
	v_permlane32_swap_b32_e32 v198, v200
	v_permlane32_swap_b32_e32 v199, v201
	v_add_co_u32_e32 v128, vcc, s61, v154
	s_nop 1
	v_addc_co_u32_e32 v129, vcc, 0, v155, vcc
	v_add_co_u32_e32 v132, vcc, s61, v156
	s_nop 1
	v_addc_co_u32_e32 v133, vcc, 0, v157, vcc
	v_add_co_u32_e32 v136, vcc, s64, v154
	global_load_dwordx4 v[128:131], v[128:129], off
	s_nop 0
	global_load_dwordx4 v[132:135], v[132:133], off
	v_addc_co_u32_e32 v137, vcc, 0, v155, vcc
	v_add_co_u32_e32 v140, vcc, s64, v156
	s_nop 1
	v_addc_co_u32_e32 v141, vcc, 0, v157, vcc
	global_load_dwordx4 v[136:139], v[136:137], off
	s_nop 0
	global_load_dwordx4 v[140:143], v[140:141], off
	ds_read_b64_tr_b16 v[154:155], v159 offset:0
	ds_read_b64_tr_b16 v[156:157], v159 offset:0x800
	ds_read_b64_tr_b16 v[202:203], v159 offset:0x1000
	ds_read_b64_tr_b16 v[204:205], v159 offset:0x1800
	ds_read_b64_tr_b16 v[206:207], v159 offset:0x2000
	ds_read_b64_tr_b16 v[208:209], v159 offset:0x2800
	ds_read_b64_tr_b16 v[210:211], v159 offset:0x3000
	ds_read_b64_tr_b16 v[212:213], v159 offset:0x3800
	s_waitcnt lgkmcnt(0)
	s_nop 0
	v_mfma_f32_32x32x16_bf16 v[0:15], v[144:147], v[154:157], v[0:15]
	ds_read_b64_tr_b16 v[154:155], v159 offset:0x200
	ds_read_b64_tr_b16 v[156:157], v159 offset:0xa00
	v_mfma_f32_32x32x16_bf16 v[0:15], v[186:189], v[202:205], v[0:15]
	ds_read_b64_tr_b16 v[202:203], v159 offset:0x1200
	ds_read_b64_tr_b16 v[204:205], v159 offset:0x1a00
	v_mfma_f32_32x32x16_bf16 v[0:15], v[194:197], v[206:209], v[0:15]
	ds_read_b64_tr_b16 v[206:207], v159 offset:0x2200
	ds_read_b64_tr_b16 v[208:209], v159 offset:0x2a00
	v_mfma_f32_32x32x16_bf16 v[0:15], v[198:201], v[210:213], v[0:15]
	ds_read_b64_tr_b16 v[210:211], v159 offset:0x3200
	ds_read_b64_tr_b16 v[212:213], v159 offset:0x3a00
	s_waitcnt lgkmcnt(0)
	v_mfma_f32_32x32x16_bf16 v[48:63], v[144:147], v[154:157], v[48:63]
	ds_read_b64_tr_b16 v[154:155], v159 offset:0x400
	ds_read_b64_tr_b16 v[156:157], v159 offset:0xc00
	v_mfma_f32_32x32x16_bf16 v[48:63], v[186:189], v[202:205], v[48:63]
	ds_read_b64_tr_b16 v[202:203], v159 offset:0x1400
	ds_read_b64_tr_b16 v[204:205], v159 offset:0x1c00
	v_mfma_f32_32x32x16_bf16 v[48:63], v[194:197], v[206:209], v[48:63]
	ds_read_b64_tr_b16 v[206:207], v159 offset:0x2400
	ds_read_b64_tr_b16 v[208:209], v159 offset:0x2c00
	v_mfma_f32_32x32x16_bf16 v[48:63], v[198:201], v[210:213], v[48:63]
	ds_read_b64_tr_b16 v[210:211], v159 offset:0x3400
	ds_read_b64_tr_b16 v[212:213], v159 offset:0x3c00
	s_waitcnt lgkmcnt(0)
	v_mfma_f32_32x32x16_bf16 v[32:47], v[144:147], v[154:157], v[32:47]
	ds_read_b64_tr_b16 v[154:155], v159 offset:0x600
	ds_read_b64_tr_b16 v[156:157], v159 offset:0xe00
	v_mfma_f32_32x32x16_bf16 v[32:47], v[186:189], v[202:205], v[32:47]
	ds_read_b64_tr_b16 v[202:203], v159 offset:0x1600
	ds_read_b64_tr_b16 v[204:205], v159 offset:0x1e00
	v_mfma_f32_32x32x16_bf16 v[32:47], v[194:197], v[206:209], v[32:47]
	ds_read_b64_tr_b16 v[206:207], v159 offset:0x2600
	ds_read_b64_tr_b16 v[208:209], v159 offset:0x2e00
	v_mfma_f32_32x32x16_bf16 v[32:47], v[198:201], v[210:213], v[32:47]
	ds_read_b64_tr_b16 v[210:211], v159 offset:0x3600
	ds_read_b64_tr_b16 v[212:213], v159 offset:0x3e00
	s_waitcnt lgkmcnt(0)
	v_mfma_f32_32x32x16_bf16 v[16:31], v[144:147], v[154:157], v[16:31]
	v_max_f32_e32 v144, v81, v81
	v_max_f32_e32 v145, v80, v80
	v_max_f32_e32 v144, v145, v144
	v_max3_f32 v144, v144, v82, v83
	v_max3_f32 v144, v144, v84, v85
	v_max3_f32 v144, v144, v86, v87
	v_max3_f32 v144, v144, v88, v89
	v_max3_f32 v144, v144, v90, v91
	v_max3_f32 v144, v144, v92, v93
	v_mfma_f32_32x32x16_bf16 v[16:31], v[186:189], v[202:205], v[16:31]
	v_max3_f32 v144, v144, v94, v95
	v_max3_f32 v144, v144, v64, v65
	v_max3_f32 v144, v144, v66, v67
	v_max3_f32 v144, v144, v68, v69
	v_max3_f32 v144, v144, v70, v71
	v_max3_f32 v144, v144, v72, v73
	v_max3_f32 v144, v144, v74, v75
	v_max3_f32 v144, v144, v76, v77
	v_mfma_f32_32x32x16_bf16 v[16:31], v[194:197], v[206:209], v[16:31]
	v_max3_f32 v144, v144, v78, v79
	v_mov_b32_e32 v145, v144
	s_nop 1
	v_permlane32_swap_b32_e32 v144, v145
	v_max_f32_e32 v145, v145, v145
	v_max_f32_e32 v144, v144, v144
	v_max_f32_e32 v144, v144, v145
	v_sub_f32_e32 v145, v144, v174
	v_cmp_ge_f32_e32 vcc, s1, v145
	v_max_f32_e32 v145, v174, v174
	v_max_f32_e32 v145, v145, v144
	v_mfma_f32_32x32x16_bf16 v[16:31], v[198:201], v[210:213], v[16:31]
	v_sub_f32_e32 v144, v174, v145
	v_mul_f32_e32 v144, 0x3e0293ee, v144
	v_exp_f32_e32 v144, v144
	s_cmp_eq_u64 vcc, exec
	s_cselect_b64 s[8:9], -1, 0
	s_barrier
	s_waitcnt vmcnt(0)
	v_cndmask_b32_e64 v144, v144, 1.0, s[8:9]
	v_cmp_gt_f32_e32 vcc, 1.0, v144
	s_waitcnt vmcnt(3)
	ds_write_b128 v164, v[128:131] offset:16384
	s_waitcnt vmcnt(2)
	ds_write_b128 v165, v[132:135] offset:16384
	s_waitcnt vmcnt(1)
	ds_write_b128 v162, v[136:139] offset:49152
	s_waitcnt vmcnt(0)
	ds_write_b128 v163, v[140:143] offset:49152
	s_cbranch_vccz .LBB0_932
	s_and_saveexec_b64 s[12:13], s[6:7]
	ds_write_b32 v151, v144 offset:128
	s_or_b64 exec, exec, s[12:13]
	s_waitcnt lgkmcnt(0)
	v_add_u32_e32 v140, s95, v150
	ds_read_b128 v[128:131], v140 offset:224
	ds_read_b128 v[132:135], v140 offset:192
	ds_read_b128 v[136:139], v140 offset:160
	ds_read_b128 v[140:143], v140 offset:128
	s_waitcnt lgkmcnt(3)
	v_pk_mul_f32 v[12:13], v[12:13], v[128:129]
	s_waitcnt lgkmcnt(2)
	v_pk_mul_f32 v[8:9], v[8:9], v[132:133]
	s_waitcnt lgkmcnt(1)
	v_pk_mul_f32 v[4:5], v[4:5], v[136:137]
	v_pk_mul_f32 v[14:15], v[14:15], v[130:131]
	v_pk_mul_f32 v[10:11], v[10:11], v[134:135]
	v_pk_mul_f32 v[6:7], v[6:7], v[138:139]
	s_waitcnt lgkmcnt(0)
	v_pk_mul_f32 v[2:3], v[2:3], v[142:143]
	v_pk_mul_f32 v[0:1], v[0:1], v[140:141]
	v_pk_mul_f32 v[60:61], v[60:61], v[128:129]
	v_pk_mul_f32 v[56:57], v[56:57], v[132:133]
	v_pk_mul_f32 v[52:53], v[52:53], v[136:137]
	v_pk_mul_f32 v[62:63], v[62:63], v[130:131]
	v_pk_mul_f32 v[58:59], v[58:59], v[134:135]
	v_pk_mul_f32 v[54:55], v[54:55], v[138:139]
	v_pk_mul_f32 v[50:51], v[50:51], v[142:143]
	v_pk_mul_f32 v[48:49], v[48:49], v[140:141]
	v_pk_mul_f32 v[44:45], v[44:45], v[128:129]
	v_pk_mul_f32 v[40:41], v[40:41], v[132:133]
	v_pk_mul_f32 v[36:37], v[36:37], v[136:137]
	v_pk_mul_f32 v[46:47], v[46:47], v[130:131]
	v_pk_mul_f32 v[42:43], v[42:43], v[134:135]
	v_pk_mul_f32 v[38:39], v[38:39], v[138:139]
	v_pk_mul_f32 v[34:35], v[34:35], v[142:143]
	v_pk_mul_f32 v[32:33], v[32:33], v[140:141]
	v_pk_mul_f32 v[28:29], v[28:29], v[128:129]
	v_pk_mul_f32 v[24:25], v[24:25], v[132:133]
	v_pk_mul_f32 v[20:21], v[20:21], v[136:137]
	v_pk_mul_f32 v[30:31], v[30:31], v[130:131]
	v_pk_mul_f32 v[26:27], v[26:27], v[134:135]
	v_pk_mul_f32 v[22:23], v[22:23], v[138:139]
	v_pk_mul_f32 v[18:19], v[18:19], v[142:143]
	v_pk_mul_f32 v[16:17], v[16:17], v[140:141]
